# speedup vs baseline: 1.0008x; 1.0008x over previous
; template <int MODE>
; __device__ __forceinline__ void attn_item(const Params& P, int b, int h, int qb, char* lds) {
;     ...
; #pragma unroll
;       for (int r = 0; r < 16; ++r) { p0[r] = __builtin_amdgcn_exp2f(p0[r]); p1[r] = __builtin_amdgcn_exp2f(p1[r]); }
;       if (MODE == 0) {
;         const int w0 = (int)((unsigned)(mcur) >> (4 * hi)), w1 = (int)((unsigned)(mcur >> 32) >> (4 * hi));
; #pragma unroll
;         for (int r = 0; r < 16; ++r) {
;           const int c = (r & 3) + 8 * (r >> 2);
;           p0[r] = __uint_as_float(__float_as_uint(p0[r]) & (unsigned)__builtin_amdgcn_sbfe(w0, c, 1));
;           p1[r] = __uint_as_float(__float_as_uint(p1[r]) & (unsigned)__builtin_amdgcn_sbfe(w1, c, 1));
;         }
;       }
;       bf16x8 pa0, pa1, pa2, pa3;
;     ...
;       PK4(p0, 0, pa0); PK4(p0, 8, pa1); PK4(p1, 0, pa2); PK4(p1, 8, pa3);
;     ...
;       if (__any(alpha < 1.f)) {
;         if (hi == 0) al_l[r32] = alpha;
;         __builtin_amdgcn_wave_barrier();
; #pragma unroll
;         for (int q = 0; q < 4; ++q) {
;           const f32x4 a4 = *(const f32x4*)(al_l + 8 * q + 4 * hi);
; #pragma unroll
;           for (int d = 0; d < 4; ++d) { o[d][q * 4 + 0] *= a4[0]; o[d][q * 4 + 1] *= a4[1]; o[d][q * 4 + 2] *= a4[2]; o[d][q * 4 + 3] *= a4[3]; }
;           ol[q * 4 + 0] *= a4[0]; ol[q * 4 + 1] *= a4[1]; ol[q * 4 + 2] *= a4[2]; ol[q * 4 + 3] *= a4[3];
;         }
;         __builtin_amdgcn_wave_barrier();
;       }
.LBB0_693:
	v_lshrrev_b32_e32 v244, v170, v166
	v_exp_f32_e32 v112, v112
	v_bfe_i32 v246, v244, 0, 1
	v_exp_f32_e32 v113, v113
	v_bfe_i32 v247, v244, 1, 1
	v_and_b32_e32 v112, v112, v246
	v_exp_f32_e32 v114, v114
	v_bfe_i32 v246, v244, 2, 1
	v_and_b32_e32 v113, v113, v247
	v_exp_f32_e32 v115, v115
	v_bfe_i32 v247, v244, 3, 1
	v_and_b32_e32 v114, v114, v246
	v_exp_f32_e32 v116, v116
	v_bfe_i32 v246, v244, 8, 1
	v_and_b32_e32 v115, v115, v247
	v_exp_f32_e32 v117, v117
	v_bfe_i32 v247, v244, 9, 1
	v_and_b32_e32 v116, v116, v246
	v_exp_f32_e32 v118, v118
	v_bfe_i32 v246, v244, 10, 1
	v_and_b32_e32 v117, v117, v247
	v_exp_f32_e32 v119, v119
	v_bfe_i32 v247, v244, 11, 1
	v_and_b32_e32 v118, v118, v246
	v_exp_f32_e32 v120, v120
	v_bfe_i32 v246, v244, 16, 1
	v_and_b32_e32 v119, v119, v247
	v_exp_f32_e32 v121, v121
	v_bfe_i32 v247, v244, 17, 1
	v_and_b32_e32 v120, v120, v246
	v_exp_f32_e32 v122, v122
	v_bfe_i32 v246, v244, 18, 1
	v_and_b32_e32 v121, v121, v247
	v_exp_f32_e32 v123, v123
	v_bfe_i32 v247, v244, 19, 1
	v_and_b32_e32 v122, v122, v246
	v_exp_f32_e32 v124, v124
	v_bfe_i32 v246, v244, 24, 1
	v_and_b32_e32 v123, v123, v247
	v_exp_f32_e32 v125, v125
	v_bfe_i32 v247, v244, 25, 1
	v_and_b32_e32 v124, v124, v246
	v_exp_f32_e32 v126, v126
	v_bfe_i32 v246, v244, 26, 1
	v_and_b32_e32 v125, v125, v247
	v_exp_f32_e32 v127, v127
	v_bfe_i32 v247, v244, 27, 1
	v_and_b32_e32 v126, v126, v246
	s_nop 0
	v_and_b32_e32 v127, v127, v247
	v_cvt_pk_bf16_f32 v2, v112, v113
	v_cvt_pk_bf16_f32 v3, v114, v115
	v_cvt_pk_bf16_f32 v4, v116, v117
	v_cvt_pk_bf16_f32 v5, v118, v119
	v_cvt_pk_bf16_f32 v6, v120, v121
	v_cvt_pk_bf16_f32 v7, v122, v123
	v_cvt_pk_bf16_f32 v8, v124, v125
	v_cvt_pk_bf16_f32 v9, v126, v127
	v_permlane32_swap_b32_e32 v2, v4
	v_permlane32_swap_b32_e32 v3, v5
	s_nop 0
	v_permlane32_swap_b32_e32 v6, v8
	v_permlane32_swap_b32_e32 v7, v9
	v_cmp_gt_f32_e32 vcc, 1.0, v0
	s_cbranch_vccz .LBB0_697
	s_and_saveexec_b64 s[0:1], s[6:7]
	ds_write_b32 v173, v0
	s_or_b64 exec, exec, s[0:1]
	ds_read_b128 v[212:215], v172 offset:96
	ds_read_b128 v[216:219], v172 offset:64
	ds_read_b128 v[220:223], v172 offset:32
	ds_read_b128 v[224:227], v172
	s_waitcnt lgkmcnt(0)
	v_pk_mul_f32 v[78:79], v[78:79], v[214:215]
	v_pk_mul_f32 v[74:75], v[74:75], v[218:219]
	v_pk_mul_f32 v[70:71], v[70:71], v[222:223]
	v_pk_mul_f32 v[66:67], v[66:67], v[226:227]
	v_pk_mul_f32 v[76:77], v[76:77], v[212:213]
	v_pk_mul_f32 v[72:73], v[72:73], v[216:217]
	v_pk_mul_f32 v[68:69], v[68:69], v[220:221]
	v_pk_mul_f32 v[64:65], v[64:65], v[224:225]
	v_pk_mul_f32 v[62:63], v[62:63], v[214:215]
	v_pk_mul_f32 v[58:59], v[58:59], v[218:219]
	v_pk_mul_f32 v[54:55], v[54:55], v[222:223]
	v_pk_mul_f32 v[50:51], v[50:51], v[226:227]
	v_pk_mul_f32 v[60:61], v[60:61], v[212:213]
	v_pk_mul_f32 v[56:57], v[56:57], v[216:217]
	v_pk_mul_f32 v[52:53], v[52:53], v[220:221]
	v_pk_mul_f32 v[48:49], v[48:49], v[224:225]
	v_pk_mul_f32 v[46:47], v[46:47], v[214:215]
	v_pk_mul_f32 v[42:43], v[42:43], v[218:219]
	v_pk_mul_f32 v[38:39], v[38:39], v[222:223]
	v_pk_mul_f32 v[34:35], v[34:35], v[226:227]
	v_pk_mul_f32 v[44:45], v[44:45], v[212:213]
	v_pk_mul_f32 v[40:41], v[40:41], v[216:217]
	v_pk_mul_f32 v[36:37], v[36:37], v[220:221]
	v_pk_mul_f32 v[32:33], v[32:33], v[224:225]
	v_pk_mul_f32 v[30:31], v[30:31], v[214:215]
	v_pk_mul_f32 v[26:27], v[26:27], v[218:219]
	v_pk_mul_f32 v[22:23], v[22:23], v[222:223]
	v_pk_mul_f32 v[18:19], v[18:19], v[226:227]
	v_pk_mul_f32 v[28:29], v[28:29], v[212:213]
	v_pk_mul_f32 v[24:25], v[24:25], v[216:217]
	v_pk_mul_f32 v[20:21], v[20:21], v[220:221]
	v_pk_mul_f32 v[16:17], v[16:17], v[224:225]
	v_pk_mul_f32 v[94:95], v[94:95], v[214:215]
	v_pk_mul_f32 v[90:91], v[90:91], v[218:219]
	v_pk_mul_f32 v[86:87], v[86:87], v[222:223]
	v_pk_mul_f32 v[82:83], v[82:83], v[226:227]
	v_pk_mul_f32 v[92:93], v[92:93], v[212:213]
	v_pk_mul_f32 v[88:89], v[88:89], v[216:217]
	v_pk_mul_f32 v[84:85], v[84:85], v[220:221]
	v_pk_mul_f32 v[80:81], v[80:81], v[224:225]
; template <int MODE>
; __device__ __forceinline__ void attn_item(const Params& P, int b, int h, int qb, char* lds) {
;     ...
; #pragma unroll
;       for (int r = 0; r < 16; ++r) { p0[r] = __builtin_amdgcn_exp2f(p0[r]); p1[r] = __builtin_amdgcn_exp2f(p1[r]); }
;       if (MODE == 0) {
;         const int w0 = (int)((unsigned)(mcur) >> (4 * hi)), w1 = (int)((unsigned)(mcur >> 32) >> (4 * hi));
; #pragma unroll
;         for (int r = 0; r < 16; ++r) {
;           const int c = (r & 3) + 8 * (r >> 2);
;           p0[r] = __uint_as_float(__float_as_uint(p0[r]) & (unsigned)__builtin_amdgcn_sbfe(w0, c, 1));
;           p1[r] = __uint_as_float(__float_as_uint(p1[r]) & (unsigned)__builtin_amdgcn_sbfe(w1, c, 1));
;         }
;       }
;       bf16x8 pa0, pa1, pa2, pa3;
;     ...
;       PK4(p0, 0, pa0); PK4(p0, 8, pa1); PK4(p1, 0, pa2); PK4(p1, 8, pa3);
;     ...
;       {
;         const int vb0 = vb_lane + buf * 16384;
;     ...
;         ol = __builtin_amdgcn_mfma_f32_32x32x16_bf16(pa0, ones, ol, 0, 0, 0);
;         ol = __builtin_amdgcn_mfma_f32_32x32x16_bf16(pa1, ones, ol, 0, 0, 0);
;         PV_D0(0); PV_D0(1);
;         ol = __builtin_amdgcn_mfma_f32_32x32x16_bf16(pa2, ones, ol, 0, 0, 0);
;         ol = __builtin_amdgcn_mfma_f32_32x32x16_bf16(pa3, ones, ol, 0, 0, 0);
;         PV_D0(2); PV_D0(3);
;     ...
;       }
.LBB0_697:
	v_add_u32_e32 v0, s9, v171
	v_mov_b32_e32 v124, s8
	v_mov_b32_e32 v125, s8
	v_mov_b32_e32 v126, s8
	v_mov_b32_e32 v127, s8
	ds_read_b64_tr_b16 v[212:213], v0 offset:0
	ds_read_b64_tr_b16 v[214:215], v0 offset:2048
	ds_read_b64_tr_b16 v[216:217], v0 offset:4096
	ds_read_b64_tr_b16 v[218:219], v0 offset:6144
	ds_read_b64_tr_b16 v[220:221], v0 offset:512
	ds_read_b64_tr_b16 v[222:223], v0 offset:2560
	ds_read_b64_tr_b16 v[224:225], v0 offset:4608
	ds_read_b64_tr_b16 v[226:227], v0 offset:6656
	ds_read_b64_tr_b16 v[228:229], v0 offset:1024
	ds_read_b64_tr_b16 v[230:231], v0 offset:3072
	ds_read_b64_tr_b16 v[232:233], v0 offset:5120
	ds_read_b64_tr_b16 v[234:235], v0 offset:7168
	ds_read_b64_tr_b16 v[236:237], v0 offset:1536
	ds_read_b64_tr_b16 v[238:239], v0 offset:3584
	v_mfma_f32_32x32x16_bf16 v[80:95], v[2:5], v[124:127], v[80:95]
	v_lshrrev_b32_e32 v245, v170, v167
	v_exp_f32_e32 v96, v96
	v_bfe_i32 v246, v245, 0, 1
	v_exp_f32_e32 v97, v97
	v_bfe_i32 v247, v245, 1, 1
	v_and_b32_e32 v96, v96, v246
	v_exp_f32_e32 v98, v98
	v_mfma_f32_32x32x16_bf16 v[80:95], v[6:9], v[124:127], v[80:95]
	v_bfe_i32 v246, v245, 2, 1
	v_and_b32_e32 v97, v97, v247
	v_exp_f32_e32 v99, v99
	v_bfe_i32 v247, v245, 3, 1
	v_and_b32_e32 v98, v98, v246
	v_exp_f32_e32 v100, v100
	v_bfe_i32 v246, v245, 8, 1
	s_waitcnt lgkmcnt(12)
	v_mfma_f32_32x32x16_bf16 v[64:79], v[2:5], v[212:215], v[64:79]
	ds_read_b64_tr_b16 v[240:241], v0 offset:5632
	ds_read_b64_tr_b16 v[242:243], v0 offset:7680
	v_and_b32_e32 v99, v99, v247
	v_exp_f32_e32 v101, v101
	v_bfe_i32 v247, v245, 9, 1
	v_and_b32_e32 v100, v100, v246
	v_exp_f32_e32 v102, v102
	v_bfe_i32 v246, v245, 10, 1
	v_and_b32_e32 v101, v101, v247
	s_waitcnt lgkmcnt(12)
	v_mfma_f32_32x32x16_bf16 v[64:79], v[6:9], v[216:219], v[64:79]
	v_exp_f32_e32 v103, v103
	v_bfe_i32 v247, v245, 11, 1
	v_and_b32_e32 v102, v102, v246
	v_exp_f32_e32 v104, v104
	v_bfe_i32 v246, v245, 16, 1
	v_and_b32_e32 v103, v103, v247
	v_exp_f32_e32 v105, v105
	s_waitcnt lgkmcnt(10)
	v_mfma_f32_32x32x16_bf16 v[48:63], v[2:5], v[220:223], v[48:63]
	v_bfe_i32 v247, v245, 17, 1
	v_and_b32_e32 v104, v104, v246
	v_exp_f32_e32 v106, v106
	v_bfe_i32 v246, v245, 18, 1
	v_and_b32_e32 v105, v105, v247
	v_exp_f32_e32 v107, v107
	v_bfe_i32 v247, v245, 19, 1
	s_waitcnt lgkmcnt(8)
	v_mfma_f32_32x32x16_bf16 v[48:63], v[6:9], v[224:227], v[48:63]
	v_and_b32_e32 v106, v106, v246
	v_exp_f32_e32 v108, v108
	v_bfe_i32 v246, v245, 24, 1
	v_and_b32_e32 v107, v107, v247
	v_exp_f32_e32 v109, v109
	v_bfe_i32 v247, v245, 25, 1
	v_and_b32_e32 v108, v108, v246
	s_waitcnt lgkmcnt(6)
	v_mfma_f32_32x32x16_bf16 v[32:47], v[2:5], v[228:231], v[32:47]
	v_exp_f32_e32 v110, v110
	v_bfe_i32 v246, v245, 26, 1
	v_and_b32_e32 v109, v109, v247
	v_exp_f32_e32 v111, v111
	v_bfe_i32 v247, v245, 27, 1
	v_and_b32_e32 v110, v110, v246
	s_nop 0
	s_waitcnt lgkmcnt(4)
	v_mfma_f32_32x32x16_bf16 v[32:47], v[6:9], v[232:235], v[32:47]
	v_and_b32_e32 v111, v111, v247
	v_cvt_pk_bf16_f32 v10, v96, v97
	v_cvt_pk_bf16_f32 v11, v98, v99
	v_cvt_pk_bf16_f32 v12, v100, v101
	v_cvt_pk_bf16_f32 v13, v102, v103
	v_cvt_pk_bf16_f32 v96, v104, v105
	v_cvt_pk_bf16_f32 v97, v106, v107
	s_waitcnt lgkmcnt(2)
	v_mfma_f32_32x32x16_bf16 v[16:31], v[2:5], v[236:239], v[16:31]
	v_cvt_pk_bf16_f32 v98, v108, v109
	v_cvt_pk_bf16_f32 v99, v110, v111
	v_permlane32_swap_b32_e32 v10, v12
	v_permlane32_swap_b32_e32 v11, v13
	s_nop 0
	v_permlane32_swap_b32_e32 v96, v98
	v_permlane32_swap_b32_e32 v97, v99
	s_waitcnt lgkmcnt(0)
	v_mfma_f32_32x32x16_bf16 v[16:31], v[6:9], v[240:243], v[16:31]
	ds_read_b64_tr_b16 v[100:101], v0 offset:8192
	ds_read_b64_tr_b16 v[102:103], v0 offset:10240
	ds_read_b64_tr_b16 v[104:105], v0 offset:12288
	ds_read_b64_tr_b16 v[106:107], v0 offset:14336
	ds_read_b64_tr_b16 v[108:109], v0 offset:8704
	ds_read_b64_tr_b16 v[110:111], v0 offset:10752
	ds_read_b64_tr_b16 v[112:113], v0 offset:12800
	ds_read_b64_tr_b16 v[114:115], v0 offset:14848
	ds_read_b64_tr_b16 v[116:117], v0 offset:9216
	ds_read_b64_tr_b16 v[118:119], v0 offset:11264
	ds_read_b64_tr_b16 v[120:121], v0 offset:13312
	ds_read_b64_tr_b16 v[122:123], v0 offset:15360
	ds_read_b64_tr_b16 v[212:213], v0 offset:9728
	ds_read_b64_tr_b16 v[214:215], v0 offset:11776
	v_mfma_f32_32x32x16_bf16 v[80:95], v[10:13], v[124:127], v[80:95]
	v_mfma_f32_32x32x16_bf16 v[80:95], v[96:99], v[124:127], v[80:95]
	s_waitcnt lgkmcnt(12)
	v_mfma_f32_32x32x16_bf16 v[64:79], v[10:13], v[100:103], v[64:79]
	ds_read_b64_tr_b16 v[216:217], v0 offset:13824
	ds_read_b64_tr_b16 v[218:219], v0 offset:15872
	s_waitcnt lgkmcnt(12)
	v_mfma_f32_32x32x16_bf16 v[64:79], v[96:99], v[104:107], v[64:79]
	s_waitcnt lgkmcnt(10)
	v_mfma_f32_32x32x16_bf16 v[48:63], v[10:13], v[108:111], v[48:63]
	s_waitcnt lgkmcnt(8)
	v_mfma_f32_32x32x16_bf16 v[48:63], v[96:99], v[112:115], v[48:63]
	s_waitcnt lgkmcnt(6)
	v_mfma_f32_32x32x16_bf16 v[32:47], v[10:13], v[116:119], v[32:47]
	s_waitcnt lgkmcnt(4)
	v_mfma_f32_32x32x16_bf16 v[32:47], v[96:99], v[120:123], v[32:47]
	s_waitcnt lgkmcnt(2)
	v_mfma_f32_32x32x16_bf16 v[16:31], v[10:13], v[212:215], v[16:31]
	s_waitcnt lgkmcnt(0)
	v_mfma_f32_32x32x16_bf16 v[16:31], v[96:99], v[216:219], v[16:31]
